# attention: the two memory cross-attention items of waves 4-7 are taken over by their partner waves 0-3 (which had ~50us slack at the end of the phase); same items, different wave
# speedup vs baseline: 1.0027x; 1.0004x over previous
; __device__ __forceinline__ void attention_phase(const Ctx& C) {
;     const int bxx = C.gw / NWAVES; const bool xmode = (C.G & 7) == 0;
;     const int x = bxx & 7, rank = xmode ? (bxx >> 3) * NWAVES + C.wave : C.gw, nrank = xmode ? (C.G >> 3) * NWAVES : C.NGW, nitem = xmode ? 1536 : 12288;
;     const int nper = (nitem + nrank - 1) / nrank, nmem_it = xmode ? (512 + nrank - 1) / nrank : 0; const bool flip = xmode && (nitem % nrank == 0); const int rot = flip ? ((C.wave * 3) >> 3) * 2 : 0;
;     for (int k0 = 0; k0 < nper; ++k0) {
;         const int kk = flip ? (k0 + rot) % nper : k0; const int i = rank + kk * nrank; if (i >= nitem) continue;
.LBB0_646:
	v_readlane_b32 s2, v254, 30
	v_readlane_b32 s3, v254, 31
	s_andn2_b64 vcc, exec, s[2:3]
	s_cbranch_vccnz .LBB0_886
	s_ashr_i32 s2, s1, 6
	s_lshl_b32 s0, s0, 3
	s_add_i32 s3, s0, s2
	s_ashr_i32 s0, s3, 31
	s_lshr_b32 s0, s0, 29
	s_add_i32 s0, s3, s0
	s_mul_i32 s1, s2, 3
	s_ashr_i32 s4, s0, 3
	s_ashr_i32 s1, s1, 2
	s_and_b32 s0, s4, -8
	s_mov_b32 s8, s1
	s_add_i32 s5, s0, s2
	v_readlane_b32 s0, v254, 3
	v_readlane_b32 s1, v254, 4
	s_and_b64 s[0:1], s[0:1], exec
	s_cselect_b32 s9, s5, s3
	s_lshl_b32 s0, s4, 10
	s_and_b32 s0, s0, 0x1800
	s_and_b32 s1, s4, 1
	s_or_b32 s71, s0, s1
	s_lshl_b32 s0, s4, 9
	s_and_b32 s72, s0, 0xe00
	s_addk_i32 s72, 0xfc00
	s_add_u32 s86, s34, 0x10200000
	s_mulk_i32 s2, 0x4100
	s_addc_u32 s87, s35, 0
	s_add_i32 s73, s2, 0
	s_add_u32 s74, s34, 0x3d00000
	s_addc_u32 s75, s35, 0
	s_add_u32 s28, s34, 0x3d80000
	s_addc_u32 s77, s35, 0
	s_add_u32 s90, s34, 0x4200000
	s_addc_u32 s91, s35, 0
	s_add_u32 s94, s34, 0x4a00000
	s_addc_u32 s95, s35, 0
	s_add_u32 s78, s34, 0x3a00000
	s_addc_u32 s79, s35, 0
	s_add_u32 s29, s34, 0x5200000
	s_addc_u32 s37, s35, 0
	s_add_u32 s59, s34, 0x5a00000
	v_and_b32_e32 v252, 63, v0
	s_addc_u32 s80, s35, 0
	s_mov_b32 s96, 0
	s_mov_b32 s100, 0
	s_branch .LBB0_651

; __device__ __forceinline__ void attention_phase(const Ctx& C) {
;     ...
;     for (int k0 = 0; k0 < nper; ++k0) {
;         const int kk = flip ? (k0 + rot) % nper : k0; const int i = rank + kk * nrank; if (i >= nitem) continue;
;         int nsa_n, mem_e;
;         if (xmode) { nsa_n = (i < 1024) ? (x >> 1) * 2048 + 2 * i + (x & 1) : -1; mem_e = x * 512 + (i - 1024); }
;         else { if (i < 8192) { const int k = i >> 11, w = i & 2047; nsa_n = k * 2048 + ((k & 1) ? 2047 - w : w); } else nsa_n = -1; mem_e = i - 8192; }
;         if (nsa_n >= 0) { const int k = nsa_n >> 11; nsa_tile(C, k >> 1, k & 1, (nsa_n & 2047) * 8); }
;         else { const int bh = mem_e >> 9; mem_tile(C, bh >> 2, bh & 3, (mem_e & 511) * 32); }
;     }
.LBB0_650:
	s_cmp_eq_u32 s100, 0
	s_cbranch_scc1 .Lbal_next
	s_cmp_eq_u32 s100, 2
	s_cbranch_scc0 .Lbal_second_done
	s_mov_b32 s100, 1
	s_add_i32 s9, s9, 4
	s_branch .LBB0_651
.Lbal_second_done:
	s_mov_b32 s100, 0
	s_add_i32 s9, s9, -4

; __device__ __forceinline__ void attention_phase(const Ctx& C) {
;     ...
;     for (int k0 = 0; k0 < nper; ++k0) {
;         const int kk = flip ? (k0 + rot) % nper : k0; const int i = rank + kk * nrank; if (i >= nitem) continue;
;         int nsa_n, mem_e;
;         if (xmode) { nsa_n = (i < 1024) ? (x >> 1) * 2048 + 2 * i + (x & 1) : -1; mem_e = x * 512 + (i - 1024); }
;         else { if (i < 8192) { const int k = i >> 11, w = i & 2047; nsa_n = k * 2048 + ((k & 1) ? 2047 - w : w); } else nsa_n = -1; mem_e = i - 8192; }
;         if (nsa_n >= 0) { const int k = nsa_n >> 11; nsa_tile(C, k >> 1, k & 1, (nsa_n & 2047) * 8); }
;         else { const int bh = mem_e >> 9; mem_tile(C, bh >> 2, bh & 3, (mem_e & 511) * 32); }
.LBB0_653:
	s_cmp_eq_u32 s0, 4
	s_cbranch_scc1 .Lbal_chk
	s_cmp_eq_u32 s0, 5
	s_cbranch_scc1 .Lbal_chk
	s_branch .Lbal_go
.Lbal_chk:
	s_cmp_eq_u32 s100, 1
	s_cbranch_scc1 .Lbal_go
	s_bitcmp1_b32 s9, 2
	s_cbranch_scc1 .LBB0_650
	s_mov_b32 s100, 2
